# SwiGLU output stored tile-major (contiguous 32KB K-tile blocks) + plain stores instead of write-through for it
# baseline (speedup 1.0000x reference)
.LBB0_173:
	v_ashrrev_i32_e32 v199, 31, v198
	v_lshl_add_u64 v[132:133], v[198:199], 2, s[50:51]
	global_load_dword v136, v[132:133], off
	global_load_dword v137, v[132:133], off offset:64
	v_and_b32_e32 v130, 63, v237
	v_and_b32_e32 v134, 64, v237
	v_lshl_or_b32 v130, v134, 8, v130
	s_mul_i32 s0, s99, 0xb0000
	s_lshl_b32 s1, s88, 15
	s_add_i32 s0, s0, s1
	s_waitcnt lgkmcnt(0)
	v_add_u32_e32 v130, s0, v130
	v_lshl_add_u32 v134, v1, 6, v130
	global_load_dword v135, v[132:133], off offset:128
	global_load_dword v138, v[132:133], off offset:192
	global_load_dword v139, v[132:133], off offset:512
	global_load_dword v140, v[132:133], off offset:576
	global_load_dword v131, v[132:133], off offset:640
	global_load_dword v130, v[132:133], off offset:704
	v_lshlrev_b32_e32 v133, 1, v134
	s_movk_i32 s0, 0x1400
	s_waitcnt vmcnt(0)
	v_fmamk_f32 v132, v136, 0x3a800000, v221
	v_rsq_f32_e32 v132, v132
	v_fmamk_f32 v136, v137, 0x3a800000, v221
	v_rsq_f32_e32 v136, v136
	v_pk_mul_f32 v[126:127], v[126:127], v[132:133] op_sel_hi:[1,0]
	v_pk_mul_f32 v[114:115], v[114:115], v[132:133] op_sel_hi:[1,0]
	v_pk_mul_f32 v[128:129], v[128:129], v[132:133] op_sel_hi:[1,0]
	v_pk_mul_f32 v[116:117], v[116:117], v[132:133] op_sel_hi:[1,0]
	v_pk_mul_f32 v[122:123], v[122:123], v[132:133] op_sel_hi:[1,0]
	v_pk_mul_f32 v[110:111], v[110:111], v[132:133] op_sel_hi:[1,0]
	v_pk_mul_f32 v[124:125], v[124:125], v[132:133] op_sel_hi:[1,0]
	v_pk_mul_f32 v[112:113], v[112:113], v[132:133] op_sel_hi:[1,0]
	v_pk_mul_f32 v[118:119], v[118:119], v[136:137] op_sel_hi:[1,0]
	v_pk_mul_f32 v[106:107], v[106:107], v[136:137] op_sel_hi:[1,0]
	v_pk_mul_f32 v[120:121], v[120:121], v[136:137] op_sel_hi:[1,0]
	v_pk_mul_f32 v[108:109], v[108:109], v[136:137] op_sel_hi:[1,0]
	v_pk_mul_f32 v[102:103], v[102:103], v[136:137] op_sel_hi:[1,0]
	v_mul_f32_e32 v132, 0xbfb8aa3b, v126
	v_pk_mul_f32 v[114:115], v[126:127], v[114:115]
	v_mul_f32_e32 v126, 0xbfb8aa3b, v127
	v_mul_f32_e32 v127, 0xbfb8aa3b, v128
	v_pk_mul_f32 v[116:117], v[128:129], v[116:117]
	v_mul_f32_e32 v128, 0xbfb8aa3b, v129
	v_mul_f32_e32 v129, 0xbfb8aa3b, v122
	v_pk_mul_f32 v[110:111], v[122:123], v[110:111]
	v_mul_f32_e32 v122, 0xbfb8aa3b, v123
	v_mul_f32_e32 v123, 0xbfb8aa3b, v124
	v_pk_mul_f32 v[112:113], v[124:125], v[112:113]
	v_mul_f32_e32 v124, 0xbfb8aa3b, v125
	v_mul_f32_e32 v125, 0xbfb8aa3b, v118
	v_pk_mul_f32 v[106:107], v[118:119], v[106:107]
	v_mul_f32_e32 v118, 0xbfb8aa3b, v119
	v_mul_f32_e32 v119, 0xbfb8aa3b, v120
	v_pk_mul_f32 v[108:109], v[120:121], v[108:109]
	v_mul_f32_e32 v120, 0xbfb8aa3b, v121
	v_mul_f32_e32 v121, 0xbfb8aa3b, v102
	v_exp_f32_e32 v132, v132
	v_exp_f32_e32 v126, v126
	v_exp_f32_e32 v127, v127
	v_exp_f32_e32 v128, v128
	v_exp_f32_e32 v129, v129
	v_exp_f32_e32 v122, v122
	v_exp_f32_e32 v123, v123
	v_exp_f32_e32 v124, v124
	v_mul_f32_e32 v137, 0xbfb8aa3b, v103
	v_exp_f32_e32 v125, v125
	v_exp_f32_e32 v118, v118
	v_exp_f32_e32 v119, v119
	v_exp_f32_e32 v120, v120
	v_exp_f32_e32 v121, v121
	v_exp_f32_e32 v137, v137
	v_add_f32_e32 v132, 1.0, v132
	v_add_f32_e32 v126, 1.0, v126
	v_add_f32_e32 v127, 1.0, v127
	v_add_f32_e32 v128, 1.0, v128
	v_add_f32_e32 v129, 1.0, v129
	v_add_f32_e32 v141, 1.0, v122
	v_add_f32_e32 v142, 1.0, v123
	v_add_f32_e32 v143, 1.0, v124
	v_add_f32_e32 v144, 1.0, v125
	v_add_f32_e32 v145, 1.0, v118
	v_add_f32_e32 v146, 1.0, v119
	v_add_f32_e32 v147, 1.0, v120
	v_add_f32_e32 v148, 1.0, v121
	v_rcp_f32_e32 v118, v132
	v_rcp_f32_e32 v119, v126
	v_rcp_f32_e32 v120, v127
	v_rcp_f32_e32 v121, v128
	v_rcp_f32_e32 v122, v129
	v_rcp_f32_e32 v123, v141
	v_rcp_f32_e32 v124, v142
	v_rcp_f32_e32 v125, v143
	v_rcp_f32_e32 v126, v144
	v_rcp_f32_e32 v127, v145
	v_rcp_f32_e32 v128, v146
	v_rcp_f32_e32 v129, v147
	v_pk_mul_f32 v[98:99], v[98:99], v[136:137] op_sel_hi:[1,0]
	v_pk_mul_f32 v[114:115], v[114:115], v[118:119]
	v_pk_mul_f32 v[98:99], v[102:103], v[98:99]
	v_pk_mul_f32 v[102:103], v[104:105], v[136:137] op_sel_hi:[1,0]
	v_pk_mul_f32 v[116:117], v[116:117], v[120:121]
	v_mul_f32_e32 v104, 0xbfb8aa3b, v102
	v_mul_f32_e32 v105, 0xbfb8aa3b, v103
	v_pk_mul_f32 v[110:111], v[110:111], v[122:123]
	v_pk_mul_f32 v[112:113], v[112:113], v[124:125]
	v_exp_f32_e32 v104, v104
	v_exp_f32_e32 v105, v105
	v_pk_mul_f32 v[118:119], v[106:107], v[126:127]
	v_pk_mul_f32 v[120:121], v[108:109], v[128:129]
	v_cvt_pk_bf16_f32 v106, v114, v115
	v_cvt_pk_bf16_f32 v107, v116, v117
	v_cvt_pk_bf16_f32 v108, v110, v111
	v_cvt_pk_bf16_f32 v109, v112, v113
	buffer_store_dwordx4 v[106:109], v133, s[20:23], 0 offen
	v_add_f32_e32 v104, 1.0, v104
	v_add_f32_e32 v105, 1.0, v105
	v_add_f32_e32 v107, 1.0, v137
	v_rcp_f32_e32 v106, v148
	v_rcp_f32_e32 v107, v107
	v_rcp_f32_e32 v104, v104
	v_rcp_f32_e32 v105, v105
	v_pk_mul_f32 v[106:107], v[98:99], v[106:107]
	v_pk_mul_f32 v[98:99], v[100:101], v[136:137] op_sel_hi:[1,0]
	s_nop 0
	v_pk_mul_f32 v[98:99], v[102:103], v[98:99]
	s_nop 0
	v_pk_mul_f32 v[102:103], v[98:99], v[104:105]
	v_fmamk_f32 v98, v135, 0x3a800000, v221
	v_rsq_f32_e32 v104, v98
	v_add_u32_e32 v105, 0x400, v134
	v_lshlrev_b32_e32 v108, 1, v105
	v_cvt_pk_bf16_f32 v98, v118, v119
	v_pk_mul_f32 v[94:95], v[94:95], v[104:105] op_sel_hi:[1,0]
	v_cvt_pk_bf16_f32 v99, v120, v121
	v_mul_f32_e32 v100, 0xbfb8aa3b, v94
	v_exp_f32_e32 v109, v100
	v_cvt_pk_bf16_f32 v100, v106, v107
	v_cvt_pk_bf16_f32 v101, v102, v103
	buffer_store_dwordx4 v[98:101], v108, s[20:23], 0 offen
	v_pk_mul_f32 v[86:87], v[86:87], v[104:105] op_sel_hi:[1,0]
	v_pk_mul_f32 v[90:91], v[90:91], v[104:105] op_sel_hi:[1,0]
	v_mul_f32_e32 v99, 0xbfb8aa3b, v95
	v_exp_f32_e32 v99, v99
	v_add_f32_e32 v98, 1.0, v109
	v_pk_mul_f32 v[86:87], v[94:95], v[86:87]
	v_rcp_f32_e32 v98, v98
	v_add_f32_e32 v94, 1.0, v99
	v_rcp_f32_e32 v99, v94
	v_pk_mul_f32 v[94:95], v[96:97], v[104:105] op_sel_hi:[1,0]
	v_pk_mul_f32 v[88:89], v[88:89], v[104:105] op_sel_hi:[1,0]
	v_mul_f32_e32 v97, 0xbfb8aa3b, v95
	v_pk_mul_f32 v[86:87], v[86:87], v[98:99]
	v_mul_f32_e32 v98, 0xbfb8aa3b, v90
	v_pk_mul_f32 v[88:89], v[94:95], v[88:89]
	v_mul_f32_e32 v95, 0xbfb8aa3b, v91
	v_pk_mul_f32 v[82:83], v[82:83], v[104:105] op_sel_hi:[1,0]
	v_exp_f32_e32 v98, v98
	v_exp_f32_e32 v95, v95
	v_pk_mul_f32 v[82:83], v[90:91], v[82:83]
	v_pk_mul_f32 v[90:91], v[92:93], v[104:105] op_sel_hi:[1,0]
	v_mul_f32_e32 v96, 0xbfb8aa3b, v94
	v_mul_f32_e32 v92, 0xbfb8aa3b, v90
	v_mul_f32_e32 v93, 0xbfb8aa3b, v91
	v_exp_f32_e32 v92, v92
	v_exp_f32_e32 v93, v93
	v_add_f32_e32 v94, 1.0, v98
	v_add_f32_e32 v95, 1.0, v95
	v_rcp_f32_e32 v94, v94
	v_rcp_f32_e32 v95, v95
	v_add_f32_e32 v92, 1.0, v92
	v_add_f32_e32 v93, 1.0, v93
	v_rcp_f32_e32 v92, v92
	v_rcp_f32_e32 v93, v93
	v_exp_f32_e32 v96, v96
	v_exp_f32_e32 v97, v97
	v_pk_mul_f32 v[94:95], v[82:83], v[94:95]
	v_pk_mul_f32 v[82:83], v[84:85], v[104:105] op_sel_hi:[1,0]
	v_add_f32_e32 v96, 1.0, v96
	v_pk_mul_f32 v[82:83], v[90:91], v[82:83]
	v_add_f32_e32 v97, 1.0, v97
	v_pk_mul_f32 v[90:91], v[82:83], v[92:93]
	v_fmamk_f32 v82, v138, 0x3a800000, v221
	v_rsq_f32_e32 v92, v82
	v_rcp_f32_e32 v96, v96
	v_rcp_f32_e32 v97, v97
	v_add_u32_e32 v93, 0x400, v105
	v_pk_mul_f32 v[78:79], v[78:79], v[92:93] op_sel_hi:[1,0]
	v_cvt_pk_bf16_f32 v82, v86, v87
	v_pk_mul_f32 v[88:89], v[88:89], v[96:97]
	v_mul_f32_e32 v84, 0xbfb8aa3b, v78
	v_lshlrev_b32_e32 v96, 1, v93
	v_cvt_pk_bf16_f32 v83, v88, v89
	v_exp_f32_e32 v86, v84
	v_cvt_pk_bf16_f32 v84, v94, v95
	v_cvt_pk_bf16_f32 v85, v90, v91
	buffer_store_dwordx4 v[82:85], v96, s[20:23], 0 offen
	v_pk_mul_f32 v[70:71], v[70:71], v[92:93] op_sel_hi:[1,0]
	v_pk_mul_f32 v[74:75], v[74:75], v[92:93] op_sel_hi:[1,0]
	v_mul_f32_e32 v83, 0xbfb8aa3b, v79
	v_exp_f32_e32 v83, v83
	v_add_f32_e32 v82, 1.0, v86
	v_pk_mul_f32 v[70:71], v[78:79], v[70:71]
	v_rcp_f32_e32 v82, v82
	v_add_f32_e32 v78, 1.0, v83
	v_rcp_f32_e32 v83, v78
	v_pk_mul_f32 v[78:79], v[80:81], v[92:93] op_sel_hi:[1,0]
	v_pk_mul_f32 v[72:73], v[72:73], v[92:93] op_sel_hi:[1,0]
	v_mul_f32_e32 v81, 0xbfb8aa3b, v79
	v_pk_mul_f32 v[70:71], v[70:71], v[82:83]
	v_mul_f32_e32 v82, 0xbfb8aa3b, v74
	v_pk_mul_f32 v[72:73], v[78:79], v[72:73]
	v_mul_f32_e32 v79, 0xbfb8aa3b, v75
	v_pk_mul_f32 v[66:67], v[66:67], v[92:93] op_sel_hi:[1,0]
	v_exp_f32_e32 v82, v82
	v_exp_f32_e32 v79, v79
	v_pk_mul_f32 v[66:67], v[74:75], v[66:67]
	v_pk_mul_f32 v[74:75], v[76:77], v[92:93] op_sel_hi:[1,0]
	v_mul_f32_e32 v80, 0xbfb8aa3b, v78
	v_mul_f32_e32 v76, 0xbfb8aa3b, v74
	v_mul_f32_e32 v77, 0xbfb8aa3b, v75
	v_exp_f32_e32 v76, v76
	v_exp_f32_e32 v77, v77
	v_add_f32_e32 v78, 1.0, v82
	v_add_f32_e32 v79, 1.0, v79
	v_rcp_f32_e32 v78, v78
	v_rcp_f32_e32 v79, v79
	v_add_f32_e32 v76, 1.0, v76
	v_add_f32_e32 v77, 1.0, v77
	v_rcp_f32_e32 v76, v76
	v_rcp_f32_e32 v77, v77
	v_exp_f32_e32 v80, v80
	v_exp_f32_e32 v81, v81
	v_pk_mul_f32 v[78:79], v[66:67], v[78:79]
	v_pk_mul_f32 v[66:67], v[68:69], v[92:93] op_sel_hi:[1,0]
	v_add_f32_e32 v80, 1.0, v80
	v_pk_mul_f32 v[66:67], v[74:75], v[66:67]
	v_add_f32_e32 v81, 1.0, v81
	v_pk_mul_f32 v[74:75], v[66:67], v[76:77]
	v_fmamk_f32 v66, v139, 0x3a800000, v221
	v_rsq_f32_e32 v76, v66
	v_rcp_f32_e32 v80, v80
	v_rcp_f32_e32 v81, v81
	v_add_u32_e32 v77, 0x400, v93
	v_pk_mul_f32 v[62:63], v[62:63], v[76:77] op_sel_hi:[1,0]
	v_cvt_pk_bf16_f32 v66, v70, v71
	v_pk_mul_f32 v[72:73], v[72:73], v[80:81]
	v_mul_f32_e32 v68, 0xbfb8aa3b, v62
	v_lshlrev_b32_e32 v80, 1, v77
	v_cvt_pk_bf16_f32 v67, v72, v73
	v_exp_f32_e32 v70, v68
	v_cvt_pk_bf16_f32 v68, v78, v79
	v_cvt_pk_bf16_f32 v69, v74, v75
	buffer_store_dwordx4 v[66:69], v80, s[20:23], 0 offen
	v_pk_mul_f32 v[54:55], v[54:55], v[76:77] op_sel_hi:[1,0]
	v_pk_mul_f32 v[58:59], v[58:59], v[76:77] op_sel_hi:[1,0]
	v_mul_f32_e32 v67, 0xbfb8aa3b, v63
	v_exp_f32_e32 v67, v67
	v_add_f32_e32 v66, 1.0, v70
	v_pk_mul_f32 v[54:55], v[62:63], v[54:55]
	v_rcp_f32_e32 v66, v66
	v_add_f32_e32 v62, 1.0, v67
	v_rcp_f32_e32 v67, v62
	v_pk_mul_f32 v[62:63], v[64:65], v[76:77] op_sel_hi:[1,0]
	v_pk_mul_f32 v[56:57], v[56:57], v[76:77] op_sel_hi:[1,0]
	v_mul_f32_e32 v65, 0xbfb8aa3b, v63
	v_pk_mul_f32 v[54:55], v[54:55], v[66:67]
	v_mul_f32_e32 v66, 0xbfb8aa3b, v58
	v_pk_mul_f32 v[56:57], v[62:63], v[56:57]
	v_mul_f32_e32 v63, 0xbfb8aa3b, v59
	v_pk_mul_f32 v[50:51], v[50:51], v[76:77] op_sel_hi:[1,0]
	v_exp_f32_e32 v66, v66
	v_exp_f32_e32 v63, v63
	v_pk_mul_f32 v[50:51], v[58:59], v[50:51]
	v_pk_mul_f32 v[58:59], v[60:61], v[76:77] op_sel_hi:[1,0]
	v_mul_f32_e32 v64, 0xbfb8aa3b, v62
	v_mul_f32_e32 v60, 0xbfb8aa3b, v58
	v_mul_f32_e32 v61, 0xbfb8aa3b, v59
	v_exp_f32_e32 v60, v60
	v_exp_f32_e32 v61, v61
	v_add_f32_e32 v62, 1.0, v66
	v_add_f32_e32 v63, 1.0, v63
	v_rcp_f32_e32 v62, v62
	v_rcp_f32_e32 v63, v63
	v_add_f32_e32 v60, 1.0, v60
	v_add_f32_e32 v61, 1.0, v61
	v_rcp_f32_e32 v60, v60
	v_rcp_f32_e32 v61, v61
	v_exp_f32_e32 v64, v64
	v_exp_f32_e32 v65, v65
	v_pk_mul_f32 v[62:63], v[50:51], v[62:63]
	v_pk_mul_f32 v[50:51], v[52:53], v[76:77] op_sel_hi:[1,0]
	v_add_f32_e32 v64, 1.0, v64
	v_pk_mul_f32 v[50:51], v[58:59], v[50:51]
	v_add_f32_e32 v65, 1.0, v65
	v_pk_mul_f32 v[58:59], v[50:51], v[60:61]
	v_fmamk_f32 v50, v140, 0x3a800000, v221
	v_rsq_f32_e32 v60, v50
	v_rcp_f32_e32 v64, v64
	v_rcp_f32_e32 v65, v65
	v_add_u32_e32 v61, s0, v77
	v_pk_mul_f32 v[46:47], v[46:47], v[60:61] op_sel_hi:[1,0]
	v_cvt_pk_bf16_f32 v50, v54, v55
	v_pk_mul_f32 v[56:57], v[56:57], v[64:65]
	v_mul_f32_e32 v52, 0xbfb8aa3b, v46
	v_lshlrev_b32_e32 v64, 1, v61
	v_cvt_pk_bf16_f32 v51, v56, v57
	v_exp_f32_e32 v54, v52
	v_cvt_pk_bf16_f32 v52, v62, v63
	v_cvt_pk_bf16_f32 v53, v58, v59
	buffer_store_dwordx4 v[50:53], v64, s[20:23], 0 offen
	v_pk_mul_f32 v[38:39], v[38:39], v[60:61] op_sel_hi:[1,0]
	v_pk_mul_f32 v[42:43], v[42:43], v[60:61] op_sel_hi:[1,0]
	v_mul_f32_e32 v51, 0xbfb8aa3b, v47
	v_exp_f32_e32 v51, v51
	v_add_f32_e32 v50, 1.0, v54
	v_pk_mul_f32 v[38:39], v[46:47], v[38:39]
	v_rcp_f32_e32 v50, v50
	v_add_f32_e32 v46, 1.0, v51
	v_rcp_f32_e32 v51, v46
	v_pk_mul_f32 v[46:47], v[48:49], v[60:61] op_sel_hi:[1,0]
	v_pk_mul_f32 v[40:41], v[40:41], v[60:61] op_sel_hi:[1,0]
	v_mul_f32_e32 v49, 0xbfb8aa3b, v47
	v_pk_mul_f32 v[38:39], v[38:39], v[50:51]
	v_mul_f32_e32 v50, 0xbfb8aa3b, v42
	v_pk_mul_f32 v[40:41], v[46:47], v[40:41]
	v_mul_f32_e32 v47, 0xbfb8aa3b, v43
	v_pk_mul_f32 v[34:35], v[34:35], v[60:61] op_sel_hi:[1,0]
	v_exp_f32_e32 v50, v50
	v_exp_f32_e32 v47, v47
	v_pk_mul_f32 v[34:35], v[42:43], v[34:35]
	v_pk_mul_f32 v[42:43], v[44:45], v[60:61] op_sel_hi:[1,0]
	v_mul_f32_e32 v48, 0xbfb8aa3b, v46
	v_mul_f32_e32 v44, 0xbfb8aa3b, v42
	v_mul_f32_e32 v45, 0xbfb8aa3b, v43
	v_exp_f32_e32 v44, v44
	v_exp_f32_e32 v45, v45
	v_add_f32_e32 v46, 1.0, v50
	v_add_f32_e32 v47, 1.0, v47
	v_rcp_f32_e32 v46, v46
	v_rcp_f32_e32 v47, v47
	v_add_f32_e32 v44, 1.0, v44
	v_add_f32_e32 v45, 1.0, v45
	v_rcp_f32_e32 v44, v44
	v_rcp_f32_e32 v45, v45
	v_exp_f32_e32 v48, v48
	v_exp_f32_e32 v49, v49
	v_pk_mul_f32 v[46:47], v[34:35], v[46:47]
	v_pk_mul_f32 v[34:35], v[36:37], v[60:61] op_sel_hi:[1,0]
	v_add_f32_e32 v48, 1.0, v48
	v_pk_mul_f32 v[34:35], v[42:43], v[34:35]
	v_add_f32_e32 v49, 1.0, v49
	v_pk_mul_f32 v[42:43], v[34:35], v[44:45]
	v_fmamk_f32 v34, v131, 0x3a800000, v221
	v_rsq_f32_e32 v44, v34
	v_rcp_f32_e32 v48, v48
	v_rcp_f32_e32 v49, v49
	v_add_u32_e32 v45, 0x400, v61
	v_pk_mul_f32 v[30:31], v[30:31], v[44:45] op_sel_hi:[1,0]
	v_cvt_pk_bf16_f32 v34, v38, v39
	v_pk_mul_f32 v[40:41], v[40:41], v[48:49]
	v_mul_f32_e32 v36, 0xbfb8aa3b, v30
	v_lshlrev_b32_e32 v48, 1, v45
	v_cvt_pk_bf16_f32 v35, v40, v41
	v_exp_f32_e32 v38, v36
	v_cvt_pk_bf16_f32 v36, v46, v47
	v_cvt_pk_bf16_f32 v37, v42, v43
	buffer_store_dwordx4 v[34:37], v48, s[20:23], 0 offen
	v_pk_mul_f32 v[22:23], v[22:23], v[44:45] op_sel_hi:[1,0]
	v_pk_mul_f32 v[26:27], v[26:27], v[44:45] op_sel_hi:[1,0]
	v_mul_f32_e32 v35, 0xbfb8aa3b, v31
	v_exp_f32_e32 v35, v35
	v_add_f32_e32 v34, 1.0, v38
	v_pk_mul_f32 v[22:23], v[30:31], v[22:23]
	v_rcp_f32_e32 v34, v34
	v_add_f32_e32 v30, 1.0, v35
	v_rcp_f32_e32 v35, v30
	v_pk_mul_f32 v[30:31], v[32:33], v[44:45] op_sel_hi:[1,0]
	v_pk_mul_f32 v[24:25], v[24:25], v[44:45] op_sel_hi:[1,0]
	v_mul_f32_e32 v33, 0xbfb8aa3b, v31
	v_pk_mul_f32 v[22:23], v[22:23], v[34:35]
	v_mul_f32_e32 v34, 0xbfb8aa3b, v26
	v_pk_mul_f32 v[24:25], v[30:31], v[24:25]
	v_mul_f32_e32 v31, 0xbfb8aa3b, v27
	v_pk_mul_f32 v[18:19], v[18:19], v[44:45] op_sel_hi:[1,0]
	v_exp_f32_e32 v34, v34
	v_exp_f32_e32 v31, v31
	v_pk_mul_f32 v[18:19], v[26:27], v[18:19]
	v_pk_mul_f32 v[26:27], v[28:29], v[44:45] op_sel_hi:[1,0]
	v_mul_f32_e32 v32, 0xbfb8aa3b, v30
	v_mul_f32_e32 v28, 0xbfb8aa3b, v26
	v_mul_f32_e32 v29, 0xbfb8aa3b, v27
	v_exp_f32_e32 v28, v28
	v_exp_f32_e32 v29, v29
	v_add_f32_e32 v30, 1.0, v34
	v_add_f32_e32 v31, 1.0, v31
	v_rcp_f32_e32 v30, v30
	v_rcp_f32_e32 v31, v31
	v_add_f32_e32 v28, 1.0, v28
	v_add_f32_e32 v29, 1.0, v29
	v_rcp_f32_e32 v28, v28
	v_rcp_f32_e32 v29, v29
	v_exp_f32_e32 v32, v32
	v_exp_f32_e32 v33, v33
	v_pk_mul_f32 v[30:31], v[18:19], v[30:31]
	v_pk_mul_f32 v[18:19], v[20:21], v[44:45] op_sel_hi:[1,0]
	v_add_f32_e32 v32, 1.0, v32
	v_pk_mul_f32 v[18:19], v[26:27], v[18:19]
	v_add_f32_e32 v33, 1.0, v33
	v_pk_mul_f32 v[26:27], v[18:19], v[28:29]
	v_fmamk_f32 v18, v130, 0x3a800000, v221
	v_rsq_f32_e32 v28, v18
	v_rcp_f32_e32 v32, v32
	v_rcp_f32_e32 v33, v33
	v_add_u32_e32 v29, 0x400, v45
	v_pk_mul_f32 v[14:15], v[14:15], v[28:29] op_sel_hi:[1,0]
	v_cvt_pk_bf16_f32 v18, v22, v23
	v_pk_mul_f32 v[24:25], v[24:25], v[32:33]
	v_mul_f32_e32 v20, 0xbfb8aa3b, v14
	v_lshlrev_b32_e32 v32, 1, v29
	v_cvt_pk_bf16_f32 v19, v24, v25
	v_exp_f32_e32 v22, v20
	v_cvt_pk_bf16_f32 v20, v30, v31
	v_cvt_pk_bf16_f32 v21, v26, v27
	buffer_store_dwordx4 v[18:21], v32, s[20:23], 0 offen
	v_pk_mul_f32 v[6:7], v[6:7], v[28:29] op_sel_hi:[1,0]
	v_pk_mul_f32 v[10:11], v[10:11], v[28:29] op_sel_hi:[1,0]
	v_mul_f32_e32 v19, 0xbfb8aa3b, v15
	v_exp_f32_e32 v19, v19
	v_add_f32_e32 v18, 1.0, v22
	v_pk_mul_f32 v[6:7], v[14:15], v[6:7]
	v_rcp_f32_e32 v18, v18
	v_add_f32_e32 v14, 1.0, v19
	v_rcp_f32_e32 v19, v14
	v_pk_mul_f32 v[14:15], v[16:17], v[28:29] op_sel_hi:[1,0]
	v_pk_mul_f32 v[8:9], v[8:9], v[28:29] op_sel_hi:[1,0]
	v_mul_f32_e32 v17, 0xbfb8aa3b, v15
	v_pk_mul_f32 v[6:7], v[6:7], v[18:19]
	v_mul_f32_e32 v18, 0xbfb8aa3b, v10
	v_pk_mul_f32 v[8:9], v[14:15], v[8:9]
	v_mul_f32_e32 v15, 0xbfb8aa3b, v11
	v_pk_mul_f32 v[2:3], v[2:3], v[28:29] op_sel_hi:[1,0]
	v_exp_f32_e32 v18, v18
	v_exp_f32_e32 v15, v15
	v_pk_mul_f32 v[2:3], v[10:11], v[2:3]
	v_pk_mul_f32 v[10:11], v[12:13], v[28:29] op_sel_hi:[1,0]
	v_mul_f32_e32 v16, 0xbfb8aa3b, v14
	v_mul_f32_e32 v12, 0xbfb8aa3b, v10
	v_mul_f32_e32 v13, 0xbfb8aa3b, v11
	v_exp_f32_e32 v16, v16
	v_exp_f32_e32 v17, v17
	v_exp_f32_e32 v12, v12
	v_exp_f32_e32 v13, v13
	v_add_f32_e32 v14, 1.0, v18
	v_add_f32_e32 v15, 1.0, v15
	v_rcp_f32_e32 v14, v14
	v_rcp_f32_e32 v15, v15
	v_add_f32_e32 v16, 1.0, v16
	v_add_f32_e32 v17, 1.0, v17
	v_add_f32_e32 v12, 1.0, v12
	v_add_f32_e32 v13, 1.0, v13
	v_rcp_f32_e32 v16, v16
	v_rcp_f32_e32 v17, v17
	v_rcp_f32_e32 v12, v12
	v_rcp_f32_e32 v13, v13
	v_pk_mul_f32 v[14:15], v[2:3], v[14:15]
	v_pk_mul_f32 v[2:3], v[4:5], v[28:29] op_sel_hi:[1,0]
	v_pk_mul_f32 v[8:9], v[8:9], v[16:17]
	v_pk_mul_f32 v[2:3], v[10:11], v[2:3]
	v_cvt_pk_bf16_f32 v4, v14, v15
	v_pk_mul_f32 v[10:11], v[2:3], v[12:13]
	v_add_u32_e32 v12, 0x400, v29
	v_lshlrev_b32_e32 v12, 1, v12
	v_cvt_pk_bf16_f32 v2, v6, v7
	v_cvt_pk_bf16_f32 v3, v8, v9
	v_cvt_pk_bf16_f32 v5, v10, v11
	buffer_store_dwordx4 v[2:5], v12, s[20:23], 0 offen
	s_and_b64 vcc, exec, s[40:41]
	s_mov_b64 s[34:35], -1
	s_cbranch_vccnz .LBB0_161
	s_branch .LBB0_225
